# v38 + grid-size guard on the balanced phase-1 deal + last phase-2 stage skips empty token blocks + GEMM prologue loads overlapped
# speedup vs baseline: 1.0049x; 1.0017x over previous
.LBB0_193:
	s_add_i32 s42, s42, 1
	s_cmpk_eq_u32 s84, 0x100
	s_cbranch_scc1 .Lp1_bal
	s_mul_i32 s4, s42, s3
	s_mul_hi_u32 s5, s42, s84
	s_add_i32 s5, s5, s4
	s_mul_i32 s4, s42, s84
	v_readlane_b32 s20, v254, 0
	v_readlane_b32 s21, v254, 1
	s_add_u32 s20, s4, s20
	s_addc_u32 s21, s5, s34
	s_branch .Lp1_end
.Lp1_bal:
	v_readlane_b32 s20, v254, 0
	s_nop 3
	s_lshl_b32 s4, s42, 8
	s_add_i32 s4, s4, s20
	s_cmpk_lt_u32 s20, 0x8a
	s_cbranch_scc0 .Lp1_light
	s_cmp_lt_u32 s42, 8
	s_cselect_b32 s20, s4, 0x7fffffff
	s_branch .Lp1_done

.Lp1_end:
	v_cmp_gt_i64_e32 vcc, s[20:21], v[144:145]
	v_cmp_lt_i64_e64 s[4:5], s[20:21], v[142:143]
	s_cbranch_vccnz .LBB0_199
	s_ashr_i32 s16, s20, 31
	s_lshr_b32 s16, s16, 29
	s_add_i32 s18, s20, s16
	s_and_b32 s16, s18, -8
	s_sub_i32 s19, s20, s16
	s_cmp_gt_i32 s19, 2
	s_mov_b64 s[16:17], -1
	s_cbranch_scc0 .LBB0_196
	s_mul_i32 s16, s19, 0x11c
	s_or_b32 s20, s16, 3
	s_mov_b64 s[16:17], 0
